# scan phase at equal priority (s_setprio 0 at scan entry, waves 4-7 raised again after it); rest as kernel-wide static prio
# baseline (speedup 1.0000x reference)
; DI void xcd_barrier(const XcdBarrier& b) {
;     asm volatile("s_waitcnt vmcnt(0)" ::: "memory");
;     __syncthreads();
;     if (threadIdx.x == 0) {
;         unsigned* bar = b.bar;
;         __builtin_amdgcn_s_waitcnt(0);
;         unsigned nloc = b.st[0], nx = b.st[1];
;         if (nloc == 0u) { xcd_barrier_complete(bar, b.x, nloc, nx); b.st[0] = nloc; b.st[1] = nx; }
; template <class BarrierFn>
; DI void scan_phase(const Args& a, int j, char* lds, const BarrierFn& gbar) {
;     const bf16_t* Qg = (const bf16_t*)(a.ws + OFF_R1); const bf16_t* Kg = (const bf16_t*)(a.ws + OFF_R2);
;     bf16_t* Vg = (bf16_t*)(a.ws + OFF_R3); bf16_t* OBg = (bf16_t*)(a.ws + OFF_R4); float* stats = (float*)(a.ws + OFF_STATS);
;     if (gridDim.x == 256) {
;         const int u = blockIdx.x, xcd = u & 7, slot = u >> 3, pair = xcd * 4 + (slot >> 3), idx = slot & 7, b = pair >> 2, h = pair & 3, dir = idx & 1, sl = idx >> 1;
;         bf16_t* TCB = (bf16_t*)(a.ws + OFF_TCB);
;         if (dir) rt::scan2_dir<1>(Qg, Kg, Vg, OBg, TCB, stats, b, h, sl, a.in[15][j * 4 + h], lds, gbar);
;         else     rt::scan2_dir<0>(Qg, Kg, Vg, OBg, TCB, stats, b, h, sl, a.in[16][j * 4 + h], lds, gbar);
;         return;
;     }
;     gbar();
.LBB0_245:
	s_or_b64 exec, exec, s[0:1]
	v_readlane_b32 s4, v254, 8
	v_readlane_b32 s5, v254, 9
	s_mov_b64 s[0:1], -1
	s_and_b64 vcc, exec, s[4:5]
	s_waitcnt lgkmcnt(0)
	s_barrier
	s_setprio 0
	s_cbranch_vccz .LBB0_299
	s_getreg_b32 s4, hwreg(HW_REG_XCC_ID, 0, 4)
	s_waitcnt vmcnt(0)
	s_barrier
	s_mov_b64 s[0:1], exec
	v_readlane_b32 s6, v253, 5
	v_readlane_b32 s7, v253, 6
	s_and_b64 s[6:7], s[0:1], s[6:7]
	s_mov_b64 exec, s[6:7]
	s_cbranch_execz .LBB0_298
	v_readlane_b32 s5, v255, 40
	s_waitcnt vmcnt(0) expcnt(0) lgkmcnt(0)
	s_and_b32 s10, s4, 15
	v_mov_b32_e32 v0, s5
	ds_read_b32 v2, v0
	v_readlane_b32 s5, v255, 41
	s_waitcnt lgkmcnt(0)
	v_cmp_ne_u32_e32 vcc, 0, v2
	v_mov_b32_e32 v0, s5
	ds_read_b32 v0, v0
	s_cbranch_vccnz .LBB0_262
	s_mov_b32 s11, 1
	s_branch .LBB0_250

; #define GSYNC() do { XcdBarrier xb_; xb_.bar = (unsigned*)(a.ws + OFF_BAR); xb_.x = xb_xcc_id(); xb_.st = (volatile LAS unsigned*)((LAS unsigned char*)lds + LDS_MAIN); xcd_barrier(xb_); } while (0)
; __global__ void __launch_bounds__(NTHREADS, 2) fwd_megakernel(Args a) {
;     ...
;             scan_phase(a, j, (char*)lds, [&]() { GSYNC(); });
;             GSYNC();
.LBB0_457:
	v_readfirstlane_b32 s100, v252
	s_nop 3
	s_lshr_b32 s100, s100, 6
	s_cmp_ge_u32 s100, 4
	s_cbranch_scc0 .Lscanx_prio_done
	s_setprio 1
